# gate/up GEMM epilogue: row-neighbour exchange by DPP row rotates instead of 128 ds_bpermute per unit
# speedup vs baseline: 1.0119x; 1.0119x over previous
;     __device__ __forceinline__ void operator()(f32x4 (&acc)[2][2][4][2], const pg8::Unit& u, int wr, int wc, int, int) const {
;     ...
;                 for (int j = 0; j < 4; ++j) {
;                     const int lc = 8 * fq + 4 * n + j; const float w0 = lwv[lc], w1 = lwv[32 + lc], w2 = lwv[64 + lc], bb = lwv[96 + lc];
;                     float gp[4], gn[4];
; #pragma unroll
;                     for (int m = 0; m < 4; ++m) { const int gi_ = __float_as_int(acc[ai][0][m][n][j]); gp[m] = __int_as_float(__builtin_amdgcn_ds_bpermute(lprev4, gi_)); gn[m] = __int_as_float(__builtin_amdgcn_ds_bpermute(lnext4, gi_)); }
;                     float pre0 = 0.f, pre3 = 0.f;
; #pragma unroll
;                     for (int m = 0; m < 4; ++m) {
;                         const float g = acc[ai][0][m][n][j], uv = acc[ai][1][m][n][j];
;                         const float pv = (fr == 0) ? (m > 0 ? gp[m > 0 ? m - 1 : 0] : 0.f) : gp[m];
;                         const float nv = (fr == 15) ? (m < 3 ? gn[m < 3 ? m + 1 : 3] : 0.f) : gn[m];
;                         const float pre = w0 * pv + w1 * g + w2 * nv + bb;
;                         if (m == 0) pre0 = pre;
;                         if (m == 3) pre3 = pre;
;                         acc[ai][1][m][n][j] = gelu_tanh(pre) * uv;
;                     }
;                     eP[j] = efirst ? pre0 : pre3;
;                     __builtin_amdgcn_sched_barrier(0);
;                 }
; #pragma unroll
;                 for (int j = 0; j < 4; ++j) eG[j] = efirst ? acc[ai][0][0][n][j] : acc[ai][0][3][n][j];
;                 if (efirst || elast) { *(f32x4*)(sbp + eo) = eP; *(f32x4*)(sbg + eo) = eG; }
.LBB0_815:
	s_or_b64 exec, exec, s[6:7]
	s_nop 0
	v_and_b32_e32 v148, 48, v146
	v_add_u32_e32 v149, -1, v146
	v_add_u32_e32 v146, 1, v146
	v_and_or_b32 v149, v149, 15, v148
	v_and_or_b32 v146, v146, 15, v148
	v_lshl_add_u32 v196, v147, 2, s49
	v_lshlrev_b32_e32 v194, 2, v149
	v_lshlrev_b32_e32 v195, 2, v146
	ds_read2_b32 v[154:155], v196 offset1:32
	ds_read2_b32 v[156:157], v196 offset0:64 offset1:96
	v_mov_b32_dpp v212, v124 row_ror:1 row_mask:0xf bank_mask:0xf
	v_mov_b32_dpp v164, v124 row_ror:15 row_mask:0xf bank_mask:0xf
	v_mov_b32_dpp v214, v80 row_ror:1 row_mask:0xf bank_mask:0xf
	v_mov_b32_dpp v211, v80 row_ror:15 row_mask:0xf bank_mask:0xf
	v_mov_b32_dpp v220, v84 row_ror:1 row_mask:0xf bank_mask:0xf
	v_mov_b32_dpp v213, v84 row_ror:15 row_mask:0xf bank_mask:0xf
	v_mov_b32_dpp v158, v120 row_ror:1 row_mask:0xf bank_mask:0xf
	v_mov_b32_dpp v219, v120 row_ror:15 row_mask:0xf bank_mask:0xf
	s_waitcnt lgkmcnt(0)
	v_mov_b32_e32 v162, v155
	v_mov_b32_e32 v160, v157
	ds_read2_b32 v[146:147], v196 offset0:1 offset1:33
	ds_read2_b32 v[148:149], v196 offset0:65 offset1:97
	v_mov_b32_dpp v216, v125 row_ror:1 row_mask:0xf bank_mask:0xf
	v_mov_b32_dpp v167, v125 row_ror:15 row_mask:0xf bank_mask:0xf
	v_mov_b32_dpp v218, v81 row_ror:1 row_mask:0xf bank_mask:0xf
	v_mov_b32_dpp v215, v81 row_ror:15 row_mask:0xf bank_mask:0xf
	v_mov_b32_dpp v222, v85 row_ror:1 row_mask:0xf bank_mask:0xf
	v_mov_b32_dpp v217, v85 row_ror:15 row_mask:0xf bank_mask:0xf
	v_mov_b32_dpp v166, v121 row_ror:1 row_mask:0xf bank_mask:0xf
	v_mov_b32_dpp v221, v121 row_ror:15 row_mask:0xf bank_mask:0xf
	s_waitcnt lgkmcnt(0)
	v_mov_b32_e32 v155, v146
	v_mov_b32_e32 v163, v147
	s_waitcnt lgkmcnt(0)
	v_mov_b32_e32 v157, v148
	v_mov_b32_e32 v161, v149
	ds_read2_b32 v[146:147], v196 offset0:2 offset1:34
	ds_read2_b32 v[148:149], v196 offset0:66 offset1:98
	v_mov_b32_dpp v200, v126 row_ror:1 row_mask:0xf bank_mask:0xf
	v_mov_b32_dpp v165, v126 row_ror:15 row_mask:0xf bank_mask:0xf
	v_mov_b32_dpp v202, v82 row_ror:1 row_mask:0xf bank_mask:0xf
	v_mov_b32_dpp v199, v82 row_ror:15 row_mask:0xf bank_mask:0xf
	v_mov_b32_dpp v208, v86 row_ror:1 row_mask:0xf bank_mask:0xf
	v_mov_b32_dpp v201, v86 row_ror:15 row_mask:0xf bank_mask:0xf
	v_mov_b32_dpp v159, v122 row_ror:1 row_mask:0xf bank_mask:0xf
	v_mov_b32_dpp v207, v122 row_ror:15 row_mask:0xf bank_mask:0xf
	ds_read2_b32 v[168:169], v196 offset0:3 offset1:35
	ds_read2_b32 v[174:175], v196 offset0:67 offset1:99
	v_mov_b32_dpp v204, v127 row_ror:1 row_mask:0xf bank_mask:0xf
	v_mov_b32_dpp v173, v127 row_ror:15 row_mask:0xf bank_mask:0xf
	v_mov_b32_dpp v206, v83 row_ror:1 row_mask:0xf bank_mask:0xf
	v_mov_b32_dpp v203, v83 row_ror:15 row_mask:0xf bank_mask:0xf
	v_mov_b32_dpp v210, v87 row_ror:1 row_mask:0xf bank_mask:0xf
	v_mov_b32_dpp v205, v87 row_ror:15 row_mask:0xf bank_mask:0xf
	v_mov_b32_dpp v172, v123 row_ror:1 row_mask:0xf bank_mask:0xf
	v_mov_b32_dpp v209, v123 row_ror:15 row_mask:0xf bank_mask:0xf
	s_waitcnt lgkmcnt(0)
	v_mov_b32_e32 v152, v147
	v_mov_b32_e32 v150, v149
	s_waitcnt lgkmcnt(0)
	v_mov_b32_e32 v147, v168
	v_mov_b32_e32 v153, v169
	s_waitcnt lgkmcnt(0)
	v_mov_b32_e32 v149, v174
	v_mov_b32_e32 v151, v175
	v_cmp_gt_i32_e64 s[6:7], 15, v193
	s_mov_b64 s[26:27], -1
	s_and_saveexec_b64 s[28:29], s[6:7]
	v_cmp_eq_u32_e64 s[6:7], 0, v193
	s_orn2_b64 s[26:27], s[6:7], exec
	s_or_b64 exec, exec, s[28:29]
	v_cndmask_b32_e64 v169, v216, 0, s[4:5]
	v_cndmask_b32_e64 v168, v212, 0, s[4:5]
	v_cndmask_b32_e32 v175, v167, v215, vcc
	v_pk_mul_f32 v[168:169], v[154:155], v[168:169]
	v_cndmask_b32_e64 v167, v166, v222, s[4:5]
	v_cndmask_b32_e64 v166, v158, v220, s[4:5]
	v_cndmask_b32_e32 v174, v164, v211, vcc
	v_pk_fma_f32 v[168:169], v[124:125], v[162:163], v[168:169]
	v_pk_mul_f32 v[166:167], v[154:155], v[166:167]
	v_pk_fma_f32 v[168:169], v[156:157], v[174:175], v[168:169]
	v_cndmask_b32_e64 v175, v221, 0, vcc
	v_cndmask_b32_e64 v174, v219, 0, vcc
	v_pk_fma_f32 v[166:167], v[120:121], v[162:163], v[166:167]
	s_waitcnt lgkmcnt(0)
	v_cndmask_b32_e32 v179, v173, v203, vcc
	v_pk_fma_f32 v[166:167], v[156:157], v[174:175], v[166:167]
	v_cndmask_b32_e64 v175, v204, 0, s[4:5]
	v_cndmask_b32_e64 v174, v200, 0, s[4:5]
	s_waitcnt lgkmcnt(0)
	v_cndmask_b32_e64 v173, v172, v210, s[4:5]
	v_cndmask_b32_e64 v172, v159, v208, s[4:5]
	v_cndmask_b32_e32 v178, v165, v199, vcc
	v_pk_mul_f32 v[164:165], v[146:147], v[174:175]
	v_pk_mul_f32 v[172:173], v[146:147], v[172:173]
	v_pk_fma_f32 v[164:165], v[126:127], v[152:153], v[164:165]
	s_waitcnt lgkmcnt(0)
	v_cndmask_b32_e64 v159, v209, 0, vcc
	v_cndmask_b32_e64 v158, v207, 0, vcc
	v_pk_fma_f32 v[172:173], v[122:123], v[152:153], v[172:173]
	v_pk_fma_f32 v[164:165], v[148:149], v[178:179], v[164:165]
	v_pk_fma_f32 v[158:159], v[148:149], v[158:159], v[172:173]
	v_pk_add_f32 v[168:169], v[160:161], v[168:169]
	v_pk_add_f32 v[166:167], v[160:161], v[166:167]
	v_pk_add_f32 v[164:165], v[150:151], v[164:165]
	v_pk_add_f32 v[158:159], v[150:151], v[158:159]
	s_and_saveexec_b64 s[6:7], s[26:27]
	s_cbranch_execz .LBB0_819
	v_lshlrev_b64 v[172:173], 2, v[170:171]
	v_cndmask_b32_e64 v123, v123, v127, s[4:5]
	v_cndmask_b32_e64 v122, v122, v126, s[4:5]
	v_cndmask_b32_e64 v121, v121, v125, s[4:5]
	v_cndmask_b32_e64 v120, v120, v124, s[4:5]
	v_cndmask_b32_e64 v127, v159, v165, s[4:5]
	v_cndmask_b32_e64 v126, v158, v164, s[4:5]
	v_cndmask_b32_e64 v125, v167, v169, s[4:5]
	v_cndmask_b32_e64 v124, v166, v168, s[4:5]
	v_lshl_add_u64 v[174:175], s[10:11], 0, v[172:173]
	global_store_dwordx4 v[174:175], v[124:127], off
	s_nop 1
	v_lshl_add_u64 v[124:125], s[14:15], 0, v[172:173]
	global_store_dwordx4 v[124:125], v[120:123], off

;     __device__ __forceinline__ void operator()(f32x4 (&acc)[2][2][4][2], const pg8::Unit& u, int wr, int wc, int, int) const {
;     ...
; #pragma unroll
;                 for (int j = 0; j < 4; ++j) {
;                     const int lc = 8 * fq + 4 * n + j; const float w0 = lwv[lc], w1 = lwv[32 + lc], w2 = lwv[64 + lc], bb = lwv[96 + lc];
;                     float gp[4], gn[4];
; #pragma unroll
;                     for (int m = 0; m < 4; ++m) { const int gi_ = __float_as_int(acc[ai][0][m][n][j]); gp[m] = __int_as_float(__builtin_amdgcn_ds_bpermute(lprev4, gi_)); gn[m] = __int_as_float(__builtin_amdgcn_ds_bpermute(lnext4, gi_)); }
;                     float pre0 = 0.f, pre3 = 0.f;
; #pragma unroll
;                     for (int m = 0; m < 4; ++m) {
;                         const float g = acc[ai][0][m][n][j], uv = acc[ai][1][m][n][j];
;                         const float pv = (fr == 0) ? (m > 0 ? gp[m > 0 ? m - 1 : 0] : 0.f) : gp[m];
;                         const float nv = (fr == 15) ? (m < 3 ? gn[m < 3 ? m + 1 : 3] : 0.f) : gn[m];
;                         const float pre = w0 * pv + w1 * g + w2 * nv + bb;
;                         if (m == 0) pre0 = pre;
;                         if (m == 3) pre3 = pre;
;                         acc[ai][1][m][n][j] = gelu_tanh(pre) * uv;
;                     }
;                     eP[j] = efirst ? pre0 : pre3;
;                     __builtin_amdgcn_sched_barrier(0);
;                 }
; #pragma unroll
;                 for (int j = 0; j < 4; ++j) eG[j] = efirst ? acc[ai][0][0][n][j] : acc[ai][0][3][n][j];
;                 if (efirst || elast) { *(f32x4*)(sbp + eo) = eP; *(f32x4*)(sbg + eo) = eG; }
.LBB0_823:
	s_or_b64 exec, exec, s[6:7]
	ds_read2_b32 v[172:173], v196 offset0:4 offset1:36
	ds_read2_b32 v[174:175], v196 offset0:68 offset1:100
	v_mov_b32_dpp v236, v116 row_ror:1 row_mask:0xf bank_mask:0xf
	v_mov_b32_dpp v182, v116 row_ror:15 row_mask:0xf bank_mask:0xf
	v_mov_b32_dpp v238, v104 row_ror:1 row_mask:0xf bank_mask:0xf
	v_mov_b32_dpp v235, v104 row_ror:15 row_mask:0xf bank_mask:0xf
	v_mov_b32_dpp v244, v108 row_ror:1 row_mask:0xf bank_mask:0xf
	v_mov_b32_dpp v237, v108 row_ror:15 row_mask:0xf bank_mask:0xf
	v_mov_b32_dpp v177, v112 row_ror:1 row_mask:0xf bank_mask:0xf
	v_mov_b32_dpp v243, v112 row_ror:15 row_mask:0xf bank_mask:0xf
	s_waitcnt lgkmcnt(0)
	v_mov_b32_e32 v180, v173
	s_waitcnt lgkmcnt(0)
	v_mov_b32_e32 v178, v175
	ds_read2_b32 v[120:121], v196 offset0:5 offset1:37
	ds_read2_b32 v[122:123], v196 offset0:69 offset1:101
	v_mov_b32_dpp v240, v117 row_ror:1 row_mask:0xf bank_mask:0xf
	v_mov_b32_dpp v185, v117 row_ror:15 row_mask:0xf bank_mask:0xf
	v_mov_b32_dpp v242, v105 row_ror:1 row_mask:0xf bank_mask:0xf
	v_mov_b32_dpp v239, v105 row_ror:15 row_mask:0xf bank_mask:0xf
	v_mov_b32_dpp v246, v109 row_ror:1 row_mask:0xf bank_mask:0xf
	v_mov_b32_dpp v241, v109 row_ror:15 row_mask:0xf bank_mask:0xf
	v_mov_b32_dpp v184, v113 row_ror:1 row_mask:0xf bank_mask:0xf
	v_mov_b32_dpp v245, v113 row_ror:15 row_mask:0xf bank_mask:0xf
	s_waitcnt lgkmcnt(0)
	v_mov_b32_e32 v173, v120
	v_mov_b32_e32 v181, v121
	s_waitcnt lgkmcnt(0)
	v_mov_b32_e32 v175, v122
	v_mov_b32_e32 v179, v123
	ds_read2_b32 v[120:121], v196 offset0:6 offset1:38
	ds_read2_b32 v[122:123], v196 offset0:70 offset1:102
	v_mov_b32_dpp v224, v118 row_ror:1 row_mask:0xf bank_mask:0xf
	v_mov_b32_dpp v183, v118 row_ror:15 row_mask:0xf bank_mask:0xf
	v_mov_b32_dpp v226, v106 row_ror:1 row_mask:0xf bank_mask:0xf
	v_mov_b32_dpp v223, v106 row_ror:15 row_mask:0xf bank_mask:0xf
	v_mov_b32_dpp v232, v110 row_ror:1 row_mask:0xf bank_mask:0xf
	v_mov_b32_dpp v225, v110 row_ror:15 row_mask:0xf bank_mask:0xf
	v_mov_b32_dpp v247, v114 row_ror:1 row_mask:0xf bank_mask:0xf
	v_mov_b32_dpp v231, v114 row_ror:15 row_mask:0xf bank_mask:0xf
	s_waitcnt lgkmcnt(0)
	v_mov_b32_e32 v126, v121
	v_lshl_or_b32 v121, v176, 2, 28
	v_add_u32_e32 v198, s49, v121
	ds_read2_b32 v[186:187], v198 offset1:32
	ds_read2_b32 v[250:251], v198 offset0:64 offset1:96
	v_mov_b32_dpp v228, v119 row_ror:1 row_mask:0xf bank_mask:0xf
	v_mov_b32_dpp v248, v119 row_ror:15 row_mask:0xf bank_mask:0xf
	v_mov_b32_dpp v230, v107 row_ror:1 row_mask:0xf bank_mask:0xf
	v_mov_b32_dpp v227, v107 row_ror:15 row_mask:0xf bank_mask:0xf
	v_mov_b32_dpp v234, v111 row_ror:1 row_mask:0xf bank_mask:0xf
	v_mov_b32_dpp v229, v111 row_ror:15 row_mask:0xf bank_mask:0xf
	v_mov_b32_dpp v176, v115 row_ror:1 row_mask:0xf bank_mask:0xf
	v_mov_b32_dpp v233, v115 row_ror:15 row_mask:0xf bank_mask:0xf
	s_waitcnt lgkmcnt(0)
	v_mov_b32_e32 v124, v123
	s_waitcnt lgkmcnt(0)
	v_mov_b32_e32 v121, v186
	v_mov_b32_e32 v127, v187
	s_waitcnt lgkmcnt(0)
	v_mov_b32_e32 v123, v250
	v_mov_b32_e32 v125, v251
	v_cmp_gt_i32_e64 s[6:7], 15, v193
	s_mov_b64 s[26:27], -1
	s_and_saveexec_b64 s[28:29], s[6:7]
	v_cmp_eq_u32_e64 s[6:7], 0, v193
	s_orn2_b64 s[26:27], s[6:7], exec
	s_or_b64 exec, exec, s[28:29]
	v_cndmask_b32_e64 v186, v236, 0, s[4:5]
	v_cndmask_b32_e64 v187, v240, 0, s[4:5]
	v_pk_mul_f32 v[186:187], v[172:173], v[186:187]
	v_cndmask_b32_e32 v250, v182, v235, vcc
	v_cndmask_b32_e32 v251, v185, v239, vcc
	v_pk_fma_f32 v[186:187], v[116:117], v[180:181], v[186:187]
	v_cndmask_b32_e64 v185, v245, 0, vcc
	v_pk_fma_f32 v[186:187], v[174:175], v[250:251], v[186:187]
	v_cndmask_b32_e64 v250, v177, v244, s[4:5]
	v_cndmask_b32_e64 v251, v184, v246, s[4:5]
	v_pk_mul_f32 v[250:251], v[172:173], v[250:251]
	v_cndmask_b32_e64 v184, v243, 0, vcc
	v_pk_fma_f32 v[250:251], v[112:113], v[180:181], v[250:251]
	v_cndmask_b32_e32 v182, v183, v223, vcc
	v_pk_fma_f32 v[184:185], v[174:175], v[184:185], v[250:251]
	v_cndmask_b32_e64 v250, v224, 0, s[4:5]
	s_waitcnt lgkmcnt(0)
	v_cndmask_b32_e64 v251, v228, 0, s[4:5]
	s_waitcnt lgkmcnt(0)
	v_cndmask_b32_e32 v183, v248, v227, vcc
	v_pk_mul_f32 v[248:249], v[120:121], v[250:251]
	s_waitcnt lgkmcnt(0)
	v_cndmask_b32_e64 v177, v233, 0, vcc
	v_pk_fma_f32 v[248:249], v[118:119], v[126:127], v[248:249]
	v_pk_add_f32 v[186:187], v[178:179], v[186:187]
	v_pk_fma_f32 v[182:183], v[122:123], v[182:183], v[248:249]
	v_cndmask_b32_e64 v248, v247, v232, s[4:5]
	v_cndmask_b32_e64 v249, v176, v234, s[4:5]
	v_pk_mul_f32 v[248:249], v[120:121], v[248:249]
	v_cndmask_b32_e64 v176, v231, 0, vcc
	v_pk_fma_f32 v[248:249], v[114:115], v[126:127], v[248:249]
	v_pk_add_f32 v[184:185], v[178:179], v[184:185]
	v_pk_fma_f32 v[176:177], v[122:123], v[176:177], v[248:249]
	v_pk_add_f32 v[182:183], v[124:125], v[182:183]
	v_pk_add_f32 v[176:177], v[124:125], v[176:177]
	s_and_saveexec_b64 s[6:7], s[26:27]
	s_cbranch_execz .LBB0_827
	v_lshlrev_b64 v[170:171], 2, v[170:171]
	v_cndmask_b32_e64 v115, v115, v119, s[4:5]
	v_cndmask_b32_e64 v114, v114, v118, s[4:5]
	v_cndmask_b32_e64 v113, v113, v117, s[4:5]
	v_cndmask_b32_e64 v112, v112, v116, s[4:5]
	v_cndmask_b32_e64 v119, v177, v183, s[4:5]
	v_cndmask_b32_e64 v118, v176, v182, s[4:5]
	v_cndmask_b32_e64 v117, v185, v187, s[4:5]
	v_cndmask_b32_e64 v116, v184, v186, s[4:5]
	v_lshl_add_u64 v[248:249], s[10:11], 0, v[170:171]
	global_store_dwordx4 v[248:249], v[116:119], off
	s_nop 1
	v_lshl_add_u64 v[116:117], s[14:15], 0, v[170:171]
	global_store_dwordx4 v[116:117], v[112:115], off

;     __device__ __forceinline__ void operator()(f32x4 (&acc)[2][2][4][2], const pg8::Unit& u, int wr, int wc, int, int) const {
;     ...
; #pragma unroll
;                 for (int j = 0; j < 4; ++j) {
;                     const int lc = 8 * fq + 4 * n + j; const float w0 = lwv[lc], w1 = lwv[32 + lc], w2 = lwv[64 + lc], bb = lwv[96 + lc];
;                     float gp[4], gn[4];
; #pragma unroll
;                     for (int m = 0; m < 4; ++m) { const int gi_ = __float_as_int(acc[ai][0][m][n][j]); gp[m] = __int_as_float(__builtin_amdgcn_ds_bpermute(lprev4, gi_)); gn[m] = __int_as_float(__builtin_amdgcn_ds_bpermute(lnext4, gi_)); }
;                     float pre0 = 0.f, pre3 = 0.f;
; #pragma unroll
;                     for (int m = 0; m < 4; ++m) {
;                         const float g = acc[ai][0][m][n][j], uv = acc[ai][1][m][n][j];
;                         const float pv = (fr == 0) ? (m > 0 ? gp[m > 0 ? m - 1 : 0] : 0.f) : gp[m];
;                         const float nv = (fr == 15) ? (m < 3 ? gn[m < 3 ? m + 1 : 3] : 0.f) : gn[m];
;                         const float pre = w0 * pv + w1 * g + w2 * nv + bb;
;                         if (m == 0) pre0 = pre;
;                         if (m == 3) pre3 = pre;
;                         acc[ai][1][m][n][j] = gelu_tanh(pre) * uv;
;                     }
;                     eP[j] = efirst ? pre0 : pre3;
;                     __builtin_amdgcn_sched_barrier(0);
;                 }
; #pragma unroll
;                 for (int j = 0; j < 4; ++j) eG[j] = efirst ? acc[ai][0][0][n][j] : acc[ai][0][3][n][j];
;                 if (efirst || elast) { *(f32x4*)(sbp + eo) = eP; *(f32x4*)(sbg + eo) = eG; }
.LBB0_831:
	s_or_b64 exec, exec, s[6:7]
	ds_read2_b32 v[74:75], v196 offset1:32
	ds_read2_b32 v[76:77], v196 offset0:64 offset1:96
	v_mov_b32_dpp v121, v60 row_ror:1 row_mask:0xf bank_mask:0xf
	v_mov_b32_dpp v84, v60 row_ror:15 row_mask:0xf bank_mask:0xf
	v_mov_b32_dpp v123, v16 row_ror:1 row_mask:0xf bank_mask:0xf
	v_mov_b32_dpp v120, v16 row_ror:15 row_mask:0xf bank_mask:0xf
	v_mov_b32_dpp v145, v20 row_ror:1 row_mask:0xf bank_mask:0xf
	v_mov_b32_dpp v122, v20 row_ror:15 row_mask:0xf bank_mask:0xf
	v_mov_b32_dpp v78, v56 row_ror:1 row_mask:0xf bank_mask:0xf
	v_mov_b32_dpp v144, v56 row_ror:15 row_mask:0xf bank_mask:0xf
	s_waitcnt lgkmcnt(0)
	v_mov_b32_e32 v82, v75
	s_waitcnt lgkmcnt(0)
	v_mov_b32_e32 v80, v77
	ds_read2_b32 v[66:67], v196 offset0:1 offset1:33
	ds_read2_b32 v[68:69], v196 offset0:65 offset1:97
	v_mov_b32_dpp v125, v61 row_ror:1 row_mask:0xf bank_mask:0xf
	v_mov_b32_dpp v87, v61 row_ror:15 row_mask:0xf bank_mask:0xf
	v_mov_b32_dpp v127, v17 row_ror:1 row_mask:0xf bank_mask:0xf
	v_mov_b32_dpp v124, v17 row_ror:15 row_mask:0xf bank_mask:0xf
	v_mov_b32_dpp v147, v21 row_ror:1 row_mask:0xf bank_mask:0xf
	v_mov_b32_dpp v126, v21 row_ror:15 row_mask:0xf bank_mask:0xf
	v_mov_b32_dpp v86, v57 row_ror:1 row_mask:0xf bank_mask:0xf
	v_mov_b32_dpp v146, v57 row_ror:15 row_mask:0xf bank_mask:0xf
	s_waitcnt lgkmcnt(0)
	v_mov_b32_e32 v75, v66
	v_mov_b32_e32 v83, v67
	s_waitcnt lgkmcnt(0)
	v_mov_b32_e32 v77, v68
	v_mov_b32_e32 v81, v69
	ds_read2_b32 v[66:67], v196 offset0:2 offset1:34
	ds_read2_b32 v[68:69], v196 offset0:66 offset1:98
	v_mov_b32_dpp v109, v62 row_ror:1 row_mask:0xf bank_mask:0xf
	v_mov_b32_dpp v85, v62 row_ror:15 row_mask:0xf bank_mask:0xf
	v_mov_b32_dpp v111, v18 row_ror:1 row_mask:0xf bank_mask:0xf
	v_mov_b32_dpp v108, v18 row_ror:15 row_mask:0xf bank_mask:0xf
	v_mov_b32_dpp v117, v22 row_ror:1 row_mask:0xf bank_mask:0xf
	v_mov_b32_dpp v110, v22 row_ror:15 row_mask:0xf bank_mask:0xf
	v_mov_b32_dpp v79, v58 row_ror:1 row_mask:0xf bank_mask:0xf
	v_mov_b32_dpp v116, v58 row_ror:15 row_mask:0xf bank_mask:0xf
	ds_read2_b32 v[88:89], v196 offset0:3 offset1:35
	ds_read2_b32 v[94:95], v196 offset0:67 offset1:99
	v_mov_b32_dpp v113, v63 row_ror:1 row_mask:0xf bank_mask:0xf
	v_mov_b32_dpp v93, v63 row_ror:15 row_mask:0xf bank_mask:0xf
	v_mov_b32_dpp v115, v19 row_ror:1 row_mask:0xf bank_mask:0xf
	v_mov_b32_dpp v112, v19 row_ror:15 row_mask:0xf bank_mask:0xf
	v_mov_b32_dpp v119, v23 row_ror:1 row_mask:0xf bank_mask:0xf
	v_mov_b32_dpp v114, v23 row_ror:15 row_mask:0xf bank_mask:0xf
	v_mov_b32_dpp v92, v59 row_ror:1 row_mask:0xf bank_mask:0xf
	v_mov_b32_dpp v118, v59 row_ror:15 row_mask:0xf bank_mask:0xf
	s_waitcnt lgkmcnt(0)
	v_mov_b32_e32 v72, v67
	v_mov_b32_e32 v70, v69
	s_waitcnt lgkmcnt(0)
	v_mov_b32_e32 v67, v88
	v_mov_b32_e32 v73, v89
	s_waitcnt lgkmcnt(0)
	v_mov_b32_e32 v69, v94
	v_mov_b32_e32 v71, v95
	v_cmp_gt_i32_e64 s[6:7], 15, v193
	s_mov_b64 s[26:27], -1
	s_and_saveexec_b64 s[28:29], s[6:7]
	v_cmp_eq_u32_e64 s[6:7], 0, v193
	s_orn2_b64 s[26:27], s[6:7], exec
	s_or_b64 exec, exec, s[28:29]
	v_cndmask_b32_e64 v88, v121, 0, s[4:5]
	v_cndmask_b32_e64 v89, v125, 0, s[4:5]
	v_pk_mul_f32 v[88:89], v[74:75], v[88:89]
	v_cndmask_b32_e32 v94, v84, v120, vcc
	v_cndmask_b32_e32 v95, v87, v124, vcc
	v_pk_fma_f32 v[88:89], v[60:61], v[82:83], v[88:89]
	v_cndmask_b32_e64 v87, v146, 0, vcc
	v_pk_fma_f32 v[88:89], v[76:77], v[94:95], v[88:89]
	v_cndmask_b32_e64 v94, v78, v145, s[4:5]
	v_cndmask_b32_e64 v95, v86, v147, s[4:5]
	v_pk_mul_f32 v[94:95], v[74:75], v[94:95]
	v_cndmask_b32_e64 v86, v144, 0, vcc
	v_pk_fma_f32 v[94:95], v[56:57], v[82:83], v[94:95]
	v_cndmask_b32_e64 v78, v79, v117, s[4:5]
	v_pk_fma_f32 v[86:87], v[76:77], v[86:87], v[94:95]
	v_cndmask_b32_e64 v94, v109, 0, s[4:5]
	s_waitcnt lgkmcnt(0)
	v_cndmask_b32_e64 v95, v113, 0, s[4:5]
	s_waitcnt lgkmcnt(0)
	v_cndmask_b32_e64 v79, v92, v119, s[4:5]
	v_pk_mul_f32 v[94:95], v[66:67], v[94:95]
	v_pk_mul_f32 v[78:79], v[66:67], v[78:79]
	v_cndmask_b32_e32 v84, v85, v108, vcc
	v_cndmask_b32_e32 v85, v93, v112, vcc
	v_pk_fma_f32 v[94:95], v[62:63], v[72:73], v[94:95]
	v_cndmask_b32_e64 v92, v116, 0, vcc
	s_waitcnt lgkmcnt(0)
	v_cndmask_b32_e64 v93, v118, 0, vcc
	v_pk_fma_f32 v[78:79], v[58:59], v[72:73], v[78:79]
	v_pk_fma_f32 v[84:85], v[68:69], v[84:85], v[94:95]
	v_pk_fma_f32 v[78:79], v[68:69], v[92:93], v[78:79]
	v_pk_add_f32 v[88:89], v[80:81], v[88:89]
	v_pk_add_f32 v[86:87], v[80:81], v[86:87]
	v_pk_add_f32 v[84:85], v[70:71], v[84:85]
	v_pk_add_f32 v[78:79], v[70:71], v[78:79]
	s_and_saveexec_b64 s[6:7], s[26:27]
	s_cbranch_execz .LBB0_835
	v_lshlrev_b64 v[92:93], 2, v[90:91]
	v_cndmask_b32_e64 v59, v59, v63, s[4:5]
	v_cndmask_b32_e64 v58, v58, v62, s[4:5]
	v_cndmask_b32_e64 v57, v57, v61, s[4:5]
	v_cndmask_b32_e64 v56, v56, v60, s[4:5]
	v_cndmask_b32_e64 v63, v79, v85, s[4:5]
	v_cndmask_b32_e64 v62, v78, v84, s[4:5]
	v_cndmask_b32_e64 v61, v87, v89, s[4:5]
	v_cndmask_b32_e64 v60, v86, v88, s[4:5]
	v_lshl_add_u64 v[94:95], s[10:11], 0, v[92:93]
	global_store_dwordx4 v[94:95], v[60:63], off
	s_nop 1
	v_lshl_add_u64 v[60:61], s[14:15], 0, v[92:93]
	global_store_dwordx4 v[60:61], v[56:59], off

;     __device__ __forceinline__ void operator()(f32x4 (&acc)[2][2][4][2], const pg8::Unit& u, int wr, int wc, int, int) const {
;     ...
; #pragma unroll
;                 for (int j = 0; j < 4; ++j) {
;                     const int lc = 8 * fq + 4 * n + j; const float w0 = lwv[lc], w1 = lwv[32 + lc], w2 = lwv[64 + lc], bb = lwv[96 + lc];
;                     float gp[4], gn[4];
; #pragma unroll
;                     for (int m = 0; m < 4; ++m) { const int gi_ = __float_as_int(acc[ai][0][m][n][j]); gp[m] = __int_as_float(__builtin_amdgcn_ds_bpermute(lprev4, gi_)); gn[m] = __int_as_float(__builtin_amdgcn_ds_bpermute(lnext4, gi_)); }
;                     float pre0 = 0.f, pre3 = 0.f;
; #pragma unroll
;                     for (int m = 0; m < 4; ++m) {
;                         const float g = acc[ai][0][m][n][j], uv = acc[ai][1][m][n][j];
;                         const float pv = (fr == 0) ? (m > 0 ? gp[m > 0 ? m - 1 : 0] : 0.f) : gp[m];
;                         const float nv = (fr == 15) ? (m < 3 ? gn[m < 3 ? m + 1 : 3] : 0.f) : gn[m];
;                         const float pre = w0 * pv + w1 * g + w2 * nv + bb;
;                         if (m == 0) pre0 = pre;
;                         if (m == 3) pre3 = pre;
;                         acc[ai][1][m][n][j] = gelu_tanh(pre) * uv;
;                     }
;                     eP[j] = efirst ? pre0 : pre3;
;                     __builtin_amdgcn_sched_barrier(0);
;                 }
; #pragma unroll
;                 for (int j = 0; j < 4; ++j) eG[j] = efirst ? acc[ai][0][0][n][j] : acc[ai][0][3][n][j];
;                 if (efirst || elast) { *(f32x4*)(sbp + eo) = eP; *(f32x4*)(sbg + eo) = eG; }
.LBB0_839:
	s_or_b64 exec, exec, s[6:7]
	ds_read2_b32 v[92:93], v196 offset0:4 offset1:36
	ds_read2_b32 v[94:95], v196 offset0:68 offset1:100
	v_mov_b32_dpp v161, v52 row_ror:1 row_mask:0xf bank_mask:0xf
	v_mov_b32_dpp v102, v52 row_ror:15 row_mask:0xf bank_mask:0xf
	v_mov_b32_dpp v163, v40 row_ror:1 row_mask:0xf bank_mask:0xf
	v_mov_b32_dpp v160, v40 row_ror:15 row_mask:0xf bank_mask:0xf
	v_mov_b32_dpp v169, v44 row_ror:1 row_mask:0xf bank_mask:0xf
	v_mov_b32_dpp v162, v44 row_ror:15 row_mask:0xf bank_mask:0xf
	v_mov_b32_dpp v96, v48 row_ror:1 row_mask:0xf bank_mask:0xf
	v_mov_b32_dpp v168, v48 row_ror:15 row_mask:0xf bank_mask:0xf
	s_waitcnt lgkmcnt(0)
	v_mov_b32_e32 v100, v93
	s_waitcnt lgkmcnt(0)
	v_mov_b32_e32 v98, v95
	ds_read2_b32 v[56:57], v196 offset0:5 offset1:37
	ds_read2_b32 v[58:59], v196 offset0:69 offset1:101
	v_mov_b32_dpp v165, v53 row_ror:1 row_mask:0xf bank_mask:0xf
	v_mov_b32_dpp v105, v53 row_ror:15 row_mask:0xf bank_mask:0xf
	v_mov_b32_dpp v167, v41 row_ror:1 row_mask:0xf bank_mask:0xf
	v_mov_b32_dpp v164, v41 row_ror:15 row_mask:0xf bank_mask:0xf
	v_mov_b32_dpp v171, v45 row_ror:1 row_mask:0xf bank_mask:0xf
	v_mov_b32_dpp v166, v45 row_ror:15 row_mask:0xf bank_mask:0xf
	v_mov_b32_dpp v104, v49 row_ror:1 row_mask:0xf bank_mask:0xf
	v_mov_b32_dpp v170, v49 row_ror:15 row_mask:0xf bank_mask:0xf
	s_waitcnt lgkmcnt(0)
	v_mov_b32_e32 v93, v56
	v_mov_b32_e32 v101, v57
	s_waitcnt lgkmcnt(0)
	v_mov_b32_e32 v95, v58
	v_mov_b32_e32 v99, v59
	ds_read2_b32 v[56:57], v196 offset0:6 offset1:38
	ds_read2_b32 v[58:59], v196 offset0:70 offset1:102
	v_mov_b32_dpp v149, v54 row_ror:1 row_mask:0xf bank_mask:0xf
	v_mov_b32_dpp v103, v54 row_ror:15 row_mask:0xf bank_mask:0xf
	v_mov_b32_dpp v151, v42 row_ror:1 row_mask:0xf bank_mask:0xf
	v_mov_b32_dpp v148, v42 row_ror:15 row_mask:0xf bank_mask:0xf
	v_mov_b32_dpp v157, v46 row_ror:1 row_mask:0xf bank_mask:0xf
	v_mov_b32_dpp v150, v46 row_ror:15 row_mask:0xf bank_mask:0xf
	v_mov_b32_dpp v97, v50 row_ror:1 row_mask:0xf bank_mask:0xf
	v_mov_b32_dpp v156, v50 row_ror:15 row_mask:0xf bank_mask:0xf
	ds_read2_b32 v[106:107], v198 offset1:32
	ds_read2_b32 v[174:175], v198 offset0:64 offset1:96
	v_mov_b32_dpp v153, v55 row_ror:1 row_mask:0xf bank_mask:0xf
	v_mov_b32_dpp v173, v55 row_ror:15 row_mask:0xf bank_mask:0xf
	v_mov_b32_dpp v155, v43 row_ror:1 row_mask:0xf bank_mask:0xf
	v_mov_b32_dpp v152, v43 row_ror:15 row_mask:0xf bank_mask:0xf
	v_mov_b32_dpp v159, v47 row_ror:1 row_mask:0xf bank_mask:0xf
	v_mov_b32_dpp v154, v47 row_ror:15 row_mask:0xf bank_mask:0xf
	v_mov_b32_dpp v172, v51 row_ror:1 row_mask:0xf bank_mask:0xf
	v_mov_b32_dpp v158, v51 row_ror:15 row_mask:0xf bank_mask:0xf
	s_waitcnt lgkmcnt(0)
	v_mov_b32_e32 v62, v57
	v_mov_b32_e32 v60, v59
	s_waitcnt lgkmcnt(0)
	v_mov_b32_e32 v57, v106
	v_mov_b32_e32 v63, v107
	s_waitcnt lgkmcnt(0)
	v_mov_b32_e32 v59, v174
	v_mov_b32_e32 v61, v175
	v_cmp_gt_i32_e64 s[6:7], 15, v193
	s_mov_b64 s[26:27], -1
	s_and_saveexec_b64 s[28:29], s[6:7]
	v_cmp_eq_u32_e64 s[6:7], 0, v193
	s_orn2_b64 s[26:27], s[6:7], exec
	s_or_b64 exec, exec, s[28:29]
	v_cndmask_b32_e64 v106, v161, 0, s[4:5]
	v_cndmask_b32_e64 v107, v165, 0, s[4:5]
	v_pk_mul_f32 v[106:107], v[92:93], v[106:107]
	v_cndmask_b32_e32 v174, v102, v160, vcc
	v_cndmask_b32_e32 v175, v105, v164, vcc
	v_pk_fma_f32 v[106:107], v[52:53], v[100:101], v[106:107]
	v_cndmask_b32_e64 v105, v170, 0, vcc
	v_pk_fma_f32 v[106:107], v[94:95], v[174:175], v[106:107]
	v_cndmask_b32_e64 v174, v96, v169, s[4:5]
	v_cndmask_b32_e64 v175, v104, v171, s[4:5]
	v_pk_mul_f32 v[174:175], v[92:93], v[174:175]
	v_cndmask_b32_e64 v104, v168, 0, vcc
	v_pk_fma_f32 v[174:175], v[48:49], v[100:101], v[174:175]
	v_cndmask_b32_e64 v96, v97, v157, s[4:5]
	v_pk_fma_f32 v[104:105], v[94:95], v[104:105], v[174:175]
	v_cndmask_b32_e64 v174, v149, 0, s[4:5]
	s_waitcnt lgkmcnt(0)
	v_cndmask_b32_e64 v175, v153, 0, s[4:5]
	s_waitcnt lgkmcnt(0)
	v_cndmask_b32_e64 v97, v172, v159, s[4:5]
	v_pk_mul_f32 v[174:175], v[56:57], v[174:175]
	v_pk_mul_f32 v[96:97], v[56:57], v[96:97]
	v_cndmask_b32_e32 v102, v103, v148, vcc
	v_cndmask_b32_e32 v103, v173, v152, vcc
	v_pk_fma_f32 v[174:175], v[54:55], v[62:63], v[174:175]
	v_cndmask_b32_e64 v172, v156, 0, vcc
	s_waitcnt lgkmcnt(0)
	v_cndmask_b32_e64 v173, v158, 0, vcc
	v_pk_fma_f32 v[96:97], v[50:51], v[62:63], v[96:97]
	v_pk_fma_f32 v[102:103], v[58:59], v[102:103], v[174:175]
	v_pk_fma_f32 v[96:97], v[58:59], v[172:173], v[96:97]
	v_pk_add_f32 v[106:107], v[98:99], v[106:107]
	v_pk_add_f32 v[104:105], v[98:99], v[104:105]
	v_pk_add_f32 v[102:103], v[60:61], v[102:103]
	v_pk_add_f32 v[96:97], v[60:61], v[96:97]
	s_and_saveexec_b64 s[6:7], s[26:27]
	s_cbranch_execz .LBB0_806
	v_lshlrev_b64 v[90:91], 2, v[90:91]
	v_cndmask_b32_e64 v51, v51, v55, s[4:5]
	v_cndmask_b32_e64 v50, v50, v54, s[4:5]
	v_cndmask_b32_e64 v49, v49, v53, s[4:5]
	v_cndmask_b32_e64 v48, v48, v52, s[4:5]
	v_cndmask_b32_e64 v55, v97, v103, s[4:5]
	v_cndmask_b32_e64 v54, v96, v102, s[4:5]
	v_cndmask_b32_e64 v53, v105, v107, s[4:5]
	v_cndmask_b32_e64 v52, v104, v106, s[4:5]
	v_lshl_add_u64 v[172:173], s[10:11], 0, v[90:91]
	global_store_dwordx4 v[172:173], v[52:55], off
	s_nop 1
	v_lshl_add_u64 v[52:53], s[14:15], 0, v[90:91]
	global_store_dwordx4 v[52:53], v[48:51], off
	s_branch .LBB0_806
